# pp_v31 + seam poll loops without s_sleep between polls
# speedup vs baseline: 1.0029x; 1.0029x over previous
.Lfs0_loop:
	global_load_dword v2, v1, s[6:7] sc1
	s_add_u32 s11, s11, 1
	s_waitcnt vmcnt(0)
	v_readfirstlane_b32 s12, v2
	s_cmp_ge_u32 s12, s10
	s_cbranch_scc1 .Lfs0_done
	s_cmp_lt_u32 s11, 0x100000
	s_cbranch_scc1 .Lfs0_loop
